# grid barriers 2..6 share one hand-written steady-state body (static branch in, ordinal dispatch out; generation = barrier ordinal, no divisions) instead of five inlined copies
# speedup vs baseline: 1.0058x; 1.0058x over previous
; __device__ __forceinline__ void xcd_barrier(const XcdBarrier& b) {
;     asm volatile("s_waitcnt vmcnt(0)" ::: "memory");
;     __syncthreads();
;     if (threadIdx.x == 0) {
;         unsigned* bar = b.bar;
;         __builtin_amdgcn_s_waitcnt(0);
;         unsigned nloc = b.st[0], nx = b.st[1];
;     __device__ bool next(int i, Unit& u) const {
;         const long L = (long)i * G + c; if (L >= nwg) return false;
;         int wgid = (int)L; { const int q = nwg / NXCD, r = nwg % NXCD, xcd = wgid % NXCD, off = wgid / NXCD; wgid = (xcd < r ? xcd * (q + 1) : r * (q + 1) + (xcd - r) * q) + off; }
;         const int nig = wgm * nN, gid = wgid / nig, fm = gid * wgm, gsz = (nM - fm) < wgm ? (nM - fm) : wgm;
;         u.pm = fm + ((wgid % nig) % gsz); u.pn = (wgid % nig) / gsz; return true;
.LBB0_148:
	s_or_b64 exec, exec, s[30:31]
	s_waitcnt vmcnt(0)
	s_waitcnt lgkmcnt(0)
	s_barrier
	s_mov_b64 s[0:1], exec
	v_readlane_b32 s4, v240, 0
	v_readlane_b32 s5, v240, 1
	s_and_b64 s[4:5], s[0:1], s[4:5]
	s_xor_b64 s[0:1], s[4:5], s[0:1]
	s_mov_b64 exec, s[4:5]
	s_cbranch_execz .LBB0_201
	s_movk_i32 s73, 1
	s_branch .Lgb_body
.Lgb_ret_1:
.LBB0_201:
	s_or_b64 exec, exec, s[0:1]
	v_mov_b32_e32 v8, v224
	s_cmpk_lt_i32 s2, 0x280
	s_waitcnt lgkmcnt(0)
	s_barrier
	s_cselect_b64 s[6:7], -1, 0
	s_cmpk_gt_i32 s2, 0x27f
	v_readfirstlane_b32 s8, v8
	s_cbranch_scc1 .LBB0_203
	s_ashr_i32 s0, s2, 31
	s_lshr_b32 s0, s0, 29
	s_add_i32 s0, s2, s0
	s_ashr_i32 s1, s0, 3
	s_and_b32 s0, s0, -8
	s_sub_i32 s0, s2, s0
	s_cmp_lt_i32 s0, 0
	s_movk_i32 s4, 0x51
	s_cselect_b32 s4, s4, 0x50
	s_mul_i32 s0, s0, s4
	s_add_i32 s0, s0, s1
	s_mul_hi_i32 s1, s0, 0x66666667
	s_lshr_b32 s4, s1, 31
	s_ashr_i32 s1, s1, 5
	s_add_i32 s1, s1, s4
	s_lshl_b32 s4, s1, 3
	s_mulk_i32 s1, 0x50
	s_sub_i32 s0, s0, s1
	s_bfe_i32 s1, s0, 0x80000
	s_bfe_u32 s1, s1, 0x3000c
	s_add_i32 s1, s0, s1
	s_bfe_i32 s5, s1, 0x80000
	s_and_b32 s1, s1, 0xf8
	s_sub_i32 s0, s0, s1
	s_sext_i32_i16 s5, s5
	s_sext_i32_i8 s0, s0
	s_add_i32 s4, s4, s0
	s_ashr_i32 s0, s5, 3

; __device__ __forceinline__ int fresh_tid() { int t = threadIdx.x; asm volatile("" : "+v"(t)); return t; }
; __device__ __forceinline__ void xcd_barrier(const XcdBarrier& b) {
;     asm volatile("s_waitcnt vmcnt(0)" ::: "memory");
;     __syncthreads();
;     if (threadIdx.x == 0) {
;         unsigned* bar = b.bar;
;         __builtin_amdgcn_s_waitcnt(0);
;         unsigned nloc = b.st[0], nx = b.st[1];
; __device__ __forceinline__ void mixer_phase(const Params& p, unsigned char* smem) {
;     const int tid = fresh_tid(), w = tid >> 6, lane = tid & 63, fr = lane & 15, fq = lane >> 4;
;     const bf16_t* pU = (const bf16_t*)(p.ws + WS_PU); const bf16_t* pV = (const bf16_t*)(p.ws + WS_PV); const bf16_t* pBG = (const bf16_t*)(p.ws + WS_PBG); const bf16_t* pZ = (const bf16_t*)(p.ws + WS_PZ);
;     bf16_t* mA = (bf16_t*)(p.ws + WS_MA); const bf16_t* Wt = (const bf16_t*)(p.ws + WS_WTRIL);
;     bf16_t* Vs = (bf16_t*)smem;
;     for (int item = blockIdx.x; item < 256; item += gridDim.x) {
;         const int hh = item & 1, bc = item >> 1, row0 = (bc >> 4) * 2048 + (bc & 15) * 128;
; #pragma unroll
;         for (int i = 0; i < 8; ++i) { const int pi = tid + 512 * i, s = pi >> 5, c16 = pi & 31, hl = c16 >> 3, d = (c16 & 7) * 8;
;             *(uint4*)(Vs + ((hl * 128 + s) * 72 + d)) = *(const uint4*)(pV + (size_t)(row0 + s) * 512 + hh * 256 + c16 * 8); }
;         __syncthreads();
.LBB0_391:
	s_waitcnt vmcnt(0)
	s_waitcnt vmcnt(0) lgkmcnt(0)
	s_barrier
	s_mov_b64 s[0:1], exec
	v_readlane_b32 s4, v240, 0
	v_readlane_b32 s5, v240, 1
	s_and_b64 s[4:5], s[0:1], s[4:5]
	s_mov_b64 exec, s[4:5]
	s_cbranch_execz .LBB0_443
	s_movk_i32 s73, 2
	s_branch .Lgb_body
.Lgb_ret_2:
.LBB0_443:
	s_or_b64 exec, exec, s[0:1]
	s_add_u32 s0, s58, 0x7bf0000
	s_addc_u32 s1, s59, 0
	s_cmpk_lt_i32 s2, 0x100
	s_cselect_b64 s[4:5], -1, 0
	v_mov_b32_e32 v98, v224
	s_and_b64 vcc, exec, s[4:5]
	s_waitcnt lgkmcnt(0)
	s_barrier
	s_cbranch_vccz .LBB0_450
	v_and_b32_e32 v0, 31, v98
	v_lshrrev_b32_e32 v2, 1, v98
	v_lshlrev_b32_e32 v64, 4, v0
	v_mov_b32_e32 v65, 0
	v_and_b32_e32 v100, 24, v2
	v_lshl_add_u64 v[66:67], s[46:47], 0, v[64:65]
	v_lshlrev_b32_e32 v0, 4, v98
	v_lshlrev_b32_e32 v64, 1, v100
	v_and_b32_e32 v1, 0x180, v0
	v_and_b32_e32 v0, 0x70, v0
	v_lshl_add_u64 v[2:3], s[58:59], 0, v[64:65]
	s_mov_b64 s[6:7], 0x1700000
	v_ashrrev_i32_e32 v101, 5, v98
	v_add_u32_e32 v0, 16, v0
	v_lshl_add_u64 v[68:69], v[2:3], 0, s[6:7]
	s_mov_b32 s6, 0xfffff80
	v_add_u32_e32 v4, v1, v101
	s_movk_i32 s8, 0x90
	v_and_or_b32 v2, v98, s6, v100
	v_mad_u64_u32 v[70:71], s[6:7], v4, s8, v[0:1]
	v_add_u32_e32 v4, 0x200, v98
	v_ashrrev_i32_e32 v71, 5, v4
	v_add_u32_e32 v4, v1, v71
	v_mad_u64_u32 v[72:73], s[6:7], v4, s8, v[0:1]
	v_add_u32_e32 v4, 0x400, v98
	v_ashrrev_i32_e32 v73, 5, v4
	v_add_u32_e32 v4, v1, v73
	v_mad_u64_u32 v[74:75], s[6:7], v4, s8, v[0:1]
	v_add_u32_e32 v4, 0x600, v98
	v_ashrrev_i32_e32 v75, 5, v4
	v_add_u32_e32 v4, v1, v75
	v_mad_u64_u32 v[76:77], s[6:7], v4, s8, v[0:1]
	v_add_u32_e32 v4, 0x800, v98
	v_ashrrev_i32_e32 v77, 5, v4
	v_add_u32_e32 v4, v1, v77
	v_mad_u64_u32 v[78:79], s[6:7], v4, s8, v[0:1]
	v_add_u32_e32 v4, 0xa00, v98
	v_ashrrev_i32_e32 v79, 5, v4
	v_add_u32_e32 v4, v1, v79
	v_mad_u64_u32 v[80:81], s[6:7], v4, s8, v[0:1]
	v_add_u32_e32 v4, 0xc00, v98
	v_ashrrev_i32_e32 v81, 5, v4
	v_add_u32_e32 v4, v1, v81
	v_mad_u64_u32 v[82:83], s[6:7], v4, s8, v[0:1]
	v_add_u32_e32 v4, 0xe00, v98
	v_ashrrev_i32_e32 v83, 5, v4
	v_add_u32_e32 v1, v1, v83
	v_and_b32_e32 v3, 3, v98
	v_mad_u64_u32 v[84:85], s[6:7], v1, s8, v[0:1]
	v_mul_lo_u32 v0, v2, s8
	v_lshlrev_b32_e32 v2, 2, v98
	v_add_u32_e32 v0, 16, v0
	v_lshlrev_b32_e32 v1, 1, v3
	v_and_b32_e32 v2, 48, v2
	v_and_b32_e32 v64, 0x4f, v98
	v_add3_u32 v85, v0, v1, v2
	v_and_b32_e32 v0, 64, v98
	v_ashrrev_i32_e32 v99, 7, v98
	v_cmp_ne_u32_e32 vcc, 0, v0
	v_or_b32_e32 v102, 16, v64
	v_or_b32_e32 v103, 32, v64
	v_or_b32_e32 v104, 48, v64
	s_lshl_b32 s10, s2, 6
	s_lshl_b32 s11, s34, 6
	s_mov_b32 s7, 0
	s_mov_b32 s12, s2
	s_branch .LBB0_446

; __device__ __forceinline__ void xcd_barrier(const XcdBarrier& b) {
;     asm volatile("s_waitcnt vmcnt(0)" ::: "memory");
;     __syncthreads();
;     if (threadIdx.x == 0) {
;         unsigned* bar = b.bar;
;         __builtin_amdgcn_s_waitcnt(0);
;         unsigned nloc = b.st[0], nx = b.st[1];
;     __device__ bool next(int i, Unit& u) const {
;         const long L = (long)i * G + c; if (L >= nwg) return false;
;         int wgid = (int)L; { const int q = nwg / NXCD, r = nwg % NXCD, xcd = wgid % NXCD, off = wgid / NXCD; wgid = (xcd < r ? xcd * (q + 1) : r * (q + 1) + (xcd - r) * q) + off; }
;         const int nig = wgm * nN, gid = wgid / nig, fm = gid * wgm, gsz = (nM - fm) < wgm ? (nM - fm) : wgm;
;         u.pm = fm + ((wgid % nig) % gsz); u.pn = (wgid % nig) / gsz; return true;
.LBB0_460:
	s_or_b64 exec, exec, s[6:7]
	s_waitcnt vmcnt(0)
	s_barrier
	s_mov_b64 s[6:7], exec
	v_readlane_b32 s8, v240, 0
	v_readlane_b32 s9, v240, 1
	s_and_b64 s[8:9], s[6:7], s[8:9]
	s_xor_b64 s[6:7], s[8:9], s[6:7]
	s_mov_b64 exec, s[8:9]
	s_cbranch_execz .LBB0_513
	s_movk_i32 s73, 3
	s_branch .Lgb_body
.Lgb_ret_3:
.LBB0_513:
	s_or_b64 exec, exec, s[6:7]
	s_add_u32 s18, s58, 0xc9c5000
	v_mov_b32_e32 v8, v224
	v_cndmask_b32_e64 v0, 0, 1, s[4:5]
	s_waitcnt lgkmcnt(0)
	s_barrier
	s_addc_u32 s19, s59, 0
	v_cmp_ne_u32_e64 s[10:11], 1, v0
	s_andn2_b64 vcc, exec, s[4:5]
	v_readfirstlane_b32 s12, v8
	s_cbranch_vccnz .LBB0_572
	s_ashr_i32 s13, s2, 31
	s_lshr_b32 s4, s13, 29
	s_add_i32 s6, s2, s4
	s_and_b32 s4, s6, -8
	s_sub_i32 s8, s2, s4
	s_cmp_gt_i32 s8, -1
	s_cbranch_scc0 .LBB0_516
	s_lshl_b32 s7, s8, 5
	s_cbranch_execz .LBB0_517
	s_branch .LBB0_518

; __device__ __forceinline__ int fresh_tid() { int t = threadIdx.x; asm volatile("" : "+v"(t)); return t; }
; __device__ __forceinline__ unsigned xb_add(unsigned* p, unsigned v) { return __hip_atomic_fetch_add(p, v, __ATOMIC_RELAXED, __HIP_MEMORY_SCOPE_AGENT); }
; __device__ __forceinline__ void xcd_barrier(const XcdBarrier& b) {
;     asm volatile("s_waitcnt vmcnt(0)" ::: "memory");
;     __syncthreads();
;     if (threadIdx.x == 0) {
;         unsigned* bar = b.bar;
;         __builtin_amdgcn_s_waitcnt(0);
;         unsigned nloc = b.st[0], nx = b.st[1];
; __global__ __launch_bounds__(512, 2) void fwd_megakernel(Params p) {
;     ...
;     { unsigned* ready6 = (unsigned*)(p.ws + WS_CNT) + CNT_READY6 * 64;
;     ...
;       if (bid < 16) {
;           rownorm_phase<false, true>(p, p.g_ffn, 3072, 4096, true, NP, NTOK, 16);
;           asm volatile("s_waitcnt vmcnt(0)" ::: "memory"); __syncthreads();
;           if (fresh_tid() == 0) xb_add(ready6, 1u); }
.LBB0_581:
	s_waitcnt vmcnt(0)
	s_barrier
	s_mov_b64 s[0:1], exec
	v_readlane_b32 s4, v240, 0
	v_readlane_b32 s5, v240, 1
	s_and_b64 s[4:5], s[0:1], s[4:5]
	s_mov_b64 exec, s[4:5]
	s_cbranch_execz .LBB0_633
	s_movk_i32 s73, 4
	s_branch .Lgb_body
.Lgb_ret_4:
.LBB0_633:
	s_or_b64 exec, exec, s[0:1]
	s_add_u32 s24, s58, 0xc944000
	s_addc_u32 s25, s59, 0
	s_cmp_lt_i32 s2, 16
	s_cselect_b64 s[20:21], -1, 0
	s_and_b64 vcc, exec, s[20:21]
	s_waitcnt lgkmcnt(0)
	s_barrier
	s_cbranch_vccz .LBB0_653
	v_mov_b32_e32 v17, v224
	s_movk_i32 s0, 0x4080
	v_ashrrev_i32_e32 v18, 6, v17
	v_add_u32_e32 v16, s97, v18
	v_cmp_gt_i32_e32 vcc, s0, v16
	s_and_saveexec_b64 s[36:37], vcc
	s_cbranch_execz .LBB0_649
	v_lshlrev_b32_e32 v0, 3, v17
	v_and_b32_e32 v64, 0x1f8, v0
	v_lshlrev_b32_e32 v19, 2, v64
	global_load_dwordx4 v[0:3], v19, s[28:29] offset:16
	global_load_dwordx4 v[4:7], v19, s[28:29]
	global_load_dwordx4 v[8:11], v19, s[28:29] offset:2064
	global_load_dwordx4 v[12:15], v19, s[28:29] offset:2048
	v_and_b32_e32 v17, 63, v17
	v_lshlrev_b32_e32 v68, 5, v17
	v_ashrrev_i32_e32 v17, 31, v16
	v_add_u32_e32 v21, s95, v18
	v_lshlrev_b64 v[18:19], 12, v[16:17]
	v_lshl_add_u64 v[70:71], s[56:57], 0, v[18:19]
	v_add_u32_e32 v18, 0x4180, v21
	s_mov_b64 s[0:1], 0x1a70000
	v_lshlrev_b64 v[16:17], 11, v[16:17]
	v_ashrrev_i32_e32 v19, 31, v18
	v_and_b32_e32 v76, 15, v21
	v_lshlrev_b32_e32 v76, 4, v76
	v_and_b32_e32 v77, -16, v21
	v_lshl_add_u32 v76, v77, 11, v76
	v_mul_u32_u24_e32 v77, 30, v64
	v_add_u32_e32 v76, v76, v77
	v_add_u32_e32 v76, 0x3a70000, v76
	v_mov_b32_e32 v77, 0
	v_add_u32_e32 v16, 0x4100, v21
	v_lshlrev_b64 v[22:23], 12, v[18:19]
	v_lshlrev_b64 v[18:19], 11, v[18:19]
	v_ashrrev_i32_e32 v17, 31, v16
	v_lshl_add_u64 v[74:75], v[18:19], 0, s[0:1]
	v_lshlrev_b64 v[18:19], 12, v[16:17]
	v_lshlrev_b64 v[16:17], 11, v[16:17]
	v_lshl_add_u64 v[80:81], v[16:17], 0, s[0:1]
	v_add_u32_e32 v16, 0x4080, v21
	v_ashrrev_i32_e32 v17, 31, v16
	v_mov_b32_e32 v67, 0
	v_or_b32_e32 v20, 0x200, v64
	v_lshl_add_u64 v[78:79], s[56:57], 0, v[18:19]
	v_lshlrev_b64 v[18:19], 12, v[16:17]
	v_lshlrev_b64 v[16:17], 11, v[16:17]
	v_add_u32_e32 v89, 0x3e00, v21
	v_mov_b32_e32 v69, v67
	v_lshl_add_u64 v[72:73], s[56:57], 0, v[22:23]
	v_lshl_add_u64 v[82:83], s[56:57], 0, v[18:19]
	v_lshl_add_u64 v[84:85], v[16:17], 0, s[0:1]
	s_mov_b64 s[28:29], 0
	s_movk_i32 s12, 0x4000
	s_movk_i32 s13, 0x3f80
	s_movk_i32 s33, 0x3f00
	s_mov_b32 s38, 0x3a800000
	s_mov_b32 s39, 0x800000
	s_movk_i32 s60, 0x6000
	s_mov_b64 s[44:45], 0x4000
	s_mov_b64 s[46:47], 0x3000
	s_mov_b64 s[48:49], 0x400
	v_lshlrev_b32_e32 v86, 2, v20
	v_mov_b32_e32 v88, 0x358637bd
	s_movk_i32 s61, 0x3e80
	s_mov_b64 s[50:51], 0x200000
	s_movk_i32 s64, 0x3e7f
	s_mov_b64 s[52:53], s[58:59]
	s_branch .LBB0_637

; __device__ __forceinline__ int fresh_tid() { int t = threadIdx.x; asm volatile("" : "+v"(t)); return t; }
; __device__ __forceinline__ void xcd_barrier(const XcdBarrier& b) {
;     asm volatile("s_waitcnt vmcnt(0)" ::: "memory");
;     __syncthreads();
;     if (threadIdx.x == 0) {
;         unsigned* bar = b.bar;
;         __builtin_amdgcn_s_waitcnt(0);
;         unsigned nloc = b.st[0], nx = b.st[1];
; template <int KSPLIT, int BATCH, bool SHAREB = false, class Epi>
; __device__ __forceinline__ void small_gemm_w(const bf16_t* __restrict__ A, int nm16, const bf16_t* __restrict__ Bt, int N, int K, const Epi& E, int row_base, float* smem) {
;     const int tid = fresh_tid(), w = tid >> 6, lane = tid & 63, fr = lane & 15, fq = lane >> 4;
;     const int total = nm16 * (N / 16) * KSPLIT, kw = K / KSPLIT;
;     f32x4* red = (f32x4*)smem;
;     for (int base = blockIdx.x * 8; base < total; base += gridDim.x * 8) {
;         const int task = base + w; const bool valid = task < total;
;         const int tile = task / KSPLIT, ks = task % KSPLIT, m16 = tile % nm16, n16 = tile / nm16;
.LBB0_695:
	s_waitcnt vmcnt(0)
	s_barrier
	s_mov_b64 s[0:1], exec
	v_readlane_b32 s6, v240, 0
	v_readlane_b32 s7, v240, 1
	s_and_b64 s[6:7], s[0:1], s[6:7]
	s_mov_b64 exec, s[6:7]
	s_cbranch_execz .LBB0_747
	s_movk_i32 s73, 5
	s_branch .Lgb_body
.Lgb_ret_5:
.LBB0_747:
	s_or_b64 exec, exec, s[0:1]
	s_waitcnt lgkmcnt(0)
	v_mov_b32_e32 v1, v224
	s_and_b64 vcc, exec, s[4:5]
	s_barrier
	s_cbranch_vccnz .LBB0_756
	v_ashrrev_i32_e32 v7, 6, v1
	v_and_b32_e32 v2, 63, v1
	v_lshrrev_b32_e32 v0, 1, v1
	s_add_u32 s4, s58, 0xbaf0000
	v_and_b32_e32 v10, 15, v1
	v_and_b32_e32 v6, 24, v0
	v_lshl_add_u32 v11, v1, 4, 16
	v_lshl_add_u32 v1, v2, 4, 16
	v_lshlrev_b32_e32 v2, 10, v7
	s_addc_u32 s5, s59, 0
	v_mov_b32_e32 v0, 0
	s_movk_i32 s3, 0x800
	v_add_u32_e32 v12, v1, v2
	s_movk_i32 s8, 0xbfff
	s_movk_i32 s9, 0x6000
	s_movk_i32 s12, 0x5000
	v_lshlrev_b32_e32 v8, 1, v6
	s_mov_b32 s13, s95
	s_branch .LBB0_750

; __device__ __forceinline__ unsigned xb_ld(unsigned* p)              { return __hip_atomic_load(p, __ATOMIC_RELAXED, __HIP_MEMORY_SCOPE_AGENT); }
; __device__ __forceinline__ unsigned xb_add(unsigned* p, unsigned v) { return __hip_atomic_fetch_add(p, v, __ATOMIC_RELAXED, __HIP_MEMORY_SCOPE_AGENT); }
; #define XB_SPIN(cond, bar) do { unsigned _sp = 0; while (cond) { __builtin_amdgcn_s_sleep(1); \
;     if ((++_sp & 255u) == 0u) { if (xb_ld(&(bar)[XB_TMO])) break; if (_sp > XB_SPIN_CAP) { atomicAdd(&(bar)[XB_TMO], 1u); break; } } } } while (0)
; __device__ __forceinline__ void xcd_barrier(const XcdBarrier& b) {
;     asm volatile("s_waitcnt vmcnt(0)" ::: "memory");
;     __syncthreads();
;     if (threadIdx.x == 0) {
;         unsigned* bar = b.bar;
;         __builtin_amdgcn_s_waitcnt(0);
;         unsigned nloc = b.st[0], nx = b.st[1];
;         if (nloc == 0u) { xcd_barrier_complete(bar, b.x, nloc, nx); b.st[0] = nloc; b.st[1] = nx; }
;         const unsigned old = xb_add(&bar[XB_XSUB(b.x)], 1u);
;         const unsigned gen = old / nloc;
;         if (old + 1u == (gen + 1u) * nloc) {
;             __builtin_amdgcn_fence(__ATOMIC_RELEASE, "agent");
;             asm volatile("s_waitcnt vmcnt(0)" ::: "memory");
;             const unsigned og = xb_add(&bar[XB_TOP], 1u);
;             const unsigned tg = og / nx;
;             asm volatile("buffer_inv sc1" ::: "memory");
;             if (og + 1u == (tg + 1u) * nx) xb_add(&bar[XB_TOPGEN], 1u);
;             else XB_SPIN(xb_ld(&bar[XB_TOPGEN]) == tg, bar);
;             xb_add(&bar[XB_XGEN(b.x)], 1u);
;             asm volatile("s_waitcnt vmcnt(0)" ::: "memory");
;         } else {
;             asm volatile("buffer_inv sc1" ::: "memory");
;             XB_SPIN(xb_ld(&bar[XB_XGEN(b.x)]) == gen, bar);
;             asm volatile("s_waitcnt vmcnt(0)" ::: "memory");
;         }
;     }
;     __syncthreads();
; }
.Lgb_body:
	v_mov_b32_e32 v0, 0
	s_waitcnt vmcnt(0) lgkmcnt(0)
	ds_read_b32 v2, v0
	ds_read_b32 v1, v0 offset:4
	s_getreg_b32 s75, hwreg(HW_REG_XCC_ID, 0, 4)
	s_and_b32 s75, s75, 15
	s_lshl_b32 s75, s75, 8
	s_add_u32 s76, s58, 0xc938000
	s_addc_u32 s77, s59, 0
	s_add_u32 s78, s76, s75
	s_addc_u32 s79, s77, 0
	v_mov_b32_e32 v3, 0x1000
	v_mov_b32_e32 v4, 1
	s_nop 3
	global_atomic_add v3, v3, v4, s[78:79] offset:1024 sc0
	s_waitcnt lgkmcnt(0)
	s_nop 0
	v_readfirstlane_b32 s80, v2
	v_readfirstlane_b32 s81, v1
	s_add_i32 s82, s73, 1
	s_mul_i32 s83, s82, s80
	s_waitcnt vmcnt(0)
	s_nop 0
	v_readfirstlane_b32 s84, v3
	s_add_i32 s84, s84, 1
	s_cmp_lg_u32 s84, s83
	s_cbranch_scc1 .Lgb_wait
	buffer_wbl2 sc1
	s_waitcnt vmcnt(0) lgkmcnt(0)
	v_mov_b32_e32 v3, 0x3000
	v_mov_b32_e32 v4, 1
	global_atomic_add v3, v3, v4, s[76:77] offset:1024 sc0
	buffer_inv sc1
	s_mul_i32 s85, s82, s81
	s_waitcnt vmcnt(0)
	s_nop 0
	v_readfirstlane_b32 s86, v3
	s_add_i32 s86, s86, 1
	s_cmp_lg_u32 s86, s85
	s_cbranch_scc1 .Lgb_leadwait
	v_mov_b32_e32 v3, 0x3000
	global_atomic_add v3, v4, s[76:77] offset:1280
	s_mov_b64 exec, 0xffff
	v_mbcnt_lo_u32_b32 v0, -1, 0
	v_lshlrev_b32_e32 v0, 8, v0
	v_add_u32_e32 v0, 0x2400, v0
	v_mov_b32_e32 v1, 1
	global_atomic_add v0, v1, s[76:77]
	s_mov_b64 exec, 1
	s_branch .Lgb_done
.Lgb_leadwait:
	s_add_u32 s78, s76, 0x3500
	s_addc_u32 s79, s77, 0
	s_branch .Lgb_spin
.Lgb_wait:
	buffer_inv sc1
	s_add_u32 s78, s78, 0x2400
	s_addc_u32 s79, s79, 0
.Lgb_spin:
	v_mov_b32_e32 v0, 0
	s_mov_b32 s87, 0
.Lgb_loop:
	global_load_dword v1, v0, s[78:79] sc1
	s_waitcnt vmcnt(0)
	s_nop 0
	v_readfirstlane_b32 s88, v1
	s_cmp_lg_u32 s88, s73
	s_cbranch_scc1 .Lgb_done
	s_sleep 1
	s_add_i32 s87, s87, 1
	s_cmp_lt_u32 s87, 0x40000
	s_cbranch_scc1 .Lgb_loop
.Lgb_done:
	s_waitcnt vmcnt(0)
	s_cmp_eq_u32 s73, 1
	s_cbranch_scc1 .Lgb_ret_1
	s_cmp_eq_u32 s73, 2
	s_cbranch_scc1 .Lgb_ret_2
	s_cmp_eq_u32 s73, 3
	s_cbranch_scc1 .Lgb_ret_3
	s_cmp_eq_u32 s73, 4
	s_cbranch_scc1 .Lgb_ret_4
	s_branch .Lgb_ret_5
